# QKV rope epilogue: rope-table vectors loaded once per tile and kept in registers (4 head groups reuse them), no re-loads behind the stores
# baseline (speedup 1.0000x reference)
.LBB0_205:
	s_mul_hi_i32 s2, s46, 0x38e38e39
	s_lshr_b32 s3, s2, 31
	s_ashr_i32 s2, s2, 1
	s_add_i32 s60, s2, s3
	s_mul_i32 s2, s60, -9
	s_add_i32 s2, s2, s46
	s_lshl_b32 s2, s2, 8
	s_lshl_b32 s59, s55, 8
	s_or_b32 s58, s2, s68
	s_add_i32 s59, s59, s69
	s_cmpk_lt_i32 s59, 0x800
	s_mov_b64 s[2:3], -1
	s_cbranch_scc0 .LBB0_223
	s_cmpk_gt_i32 s58, 0xff
	s_cselect_b64 s[62:63], -1, 0
	s_add_i32 s2, s58, 0xffffff00
	s_lshr_b32 s22, s2, 2
	s_cmpk_lt_i32 s58, 0x100
	s_waitcnt lgkmcnt(5)
	v_mov_b32_e32 v134, v120
	v_mov_b32_e32 v135, v121
	s_waitcnt lgkmcnt(0)
	v_mov_b32_e32 v136, v122
	v_mov_b32_e32 v137, v123
	v_mov_b32_e32 v142, v124
	v_mov_b32_e32 v143, v125
	v_mov_b32_e32 v146, v126
	v_mov_b32_e32 v147, v127
	v_mov_b32_e32 v138, v112
	v_mov_b32_e32 v139, v113
	v_mov_b32_e32 v140, v114
	v_mov_b32_e32 v141, v115
	v_mov_b32_e32 v144, v116
	v_mov_b32_e32 v145, v117
	v_mov_b32_e32 v148, v118
	v_mov_b32_e32 v149, v119
	s_cbranch_scc1 .LBB0_208
	v_lshl_add_u64 v[142:143], s[22:23], 3, v[194:195]
	global_load_dwordx4 v[128:131], v[142:143], off offset:16
	global_load_dwordx4 v[132:135], v[142:143], off
	v_mov_b32_e32 v138, v120
	v_mov_b32_e32 v139, v113
	v_mov_b32_e32 v140, v112
	v_mov_b32_e32 v141, v121
	v_mov_b32_e32 v150, v124
	v_mov_b32_e32 v151, v117
	v_mov_b32_e32 v148, v116
	v_mov_b32_e32 v149, v125
	s_waitcnt vmcnt(1)
	v_mov_b32_e32 v240, v128
	v_mov_b32_e32 v241, v129
	v_mov_b32_e32 v242, v130
	v_mov_b32_e32 v243, v131
	v_mov_b32_e32 v144, v129
	s_waitcnt vmcnt(0)
	v_mov_b32_e32 v244, v132
	v_mov_b32_e32 v245, v133
	v_mov_b32_e32 v246, v134
	v_mov_b32_e32 v247, v135
	v_mov_b32_e32 v146, v132
	v_mov_b32_e32 v147, v135
	v_mov_b32_e32 v136, v133
	v_mov_b32_e32 v137, v134
	v_pk_mul_f32 v[146:147], v[138:139], v[146:147]
	v_mov_b32_e32 v138, v133
	v_mov_b32_e32 v139, v135
	v_mov_b32_e32 v133, v134
	v_pk_fma_f32 v[134:135], v[140:141], v[136:137], v[146:147]
	v_mov_b32_e32 v136, v122
	v_mov_b32_e32 v137, v115
	v_mov_b32_e32 v140, v128
	v_mov_b32_e32 v141, v131
	v_pk_mul_f32 v[138:139], v[120:121], v[138:139]
	v_pk_mul_f32 v[136:137], v[136:137], v[140:141]
	v_mov_b32_e32 v140, v129
	v_mov_b32_e32 v145, v130
	v_pk_fma_f32 v[138:139], v[112:113], v[132:133], v[138:139] neg_lo:[0,0,1] neg_hi:[0,0,1]
	v_mov_b32_e32 v132, v114
	v_mov_b32_e32 v133, v123
	v_pk_mul_f32 v[140:141], v[122:123], v[140:141]
	v_mov_b32_e32 v129, v130
	v_pk_fma_f32 v[140:141], v[114:115], v[128:129], v[140:141] neg_lo:[0,0,1] neg_hi:[0,0,1]
	v_pk_fma_f32 v[136:137], v[132:133], v[144:145], v[136:137]
	global_load_dwordx4 v[128:131], v[142:143], off offset:80
	s_nop 0
	global_load_dwordx4 v[142:145], v[142:143], off offset:64
	s_waitcnt vmcnt(1)
	v_mov_b32_e32 v248, v128
	v_mov_b32_e32 v249, v129
	v_mov_b32_e32 v250, v130
	v_mov_b32_e32 v251, v131
	v_mov_b32_e32 v146, v129
	s_waitcnt vmcnt(0)
	v_mov_b32_e32 v252, v142
	v_mov_b32_e32 v253, v143
	v_mov_b32_e32 v254, v144
	v_mov_b32_e32 v255, v145
	v_mov_b32_e32 v152, v142
	v_mov_b32_e32 v153, v145
	v_pk_mul_f32 v[150:151], v[150:151], v[152:153]
	v_mov_b32_e32 v152, v143
	v_mov_b32_e32 v132, v143
	v_mov_b32_e32 v133, v144
	v_pk_mul_f32 v[152:153], v[124:125], v[152:153]
	v_mov_b32_e32 v143, v144
	v_pk_fma_f32 v[144:145], v[116:117], v[142:143], v[152:153] neg_lo:[0,0,1] neg_hi:[0,0,1]
	v_pk_fma_f32 v[142:143], v[148:149], v[132:133], v[150:151]
	v_mov_b32_e32 v148, v126
	v_mov_b32_e32 v149, v119
	v_mov_b32_e32 v150, v128
	v_mov_b32_e32 v151, v131
	v_pk_mul_f32 v[150:151], v[148:149], v[150:151]
	v_mov_b32_e32 v148, v129
	v_mov_b32_e32 v149, v131
	v_mov_b32_e32 v147, v130
	v_mov_b32_e32 v132, v118
	v_mov_b32_e32 v133, v127
	v_pk_mul_f32 v[148:149], v[126:127], v[148:149]
	v_mov_b32_e32 v129, v130
	v_pk_fma_f32 v[148:149], v[118:119], v[128:129], v[148:149] neg_lo:[0,0,1] neg_hi:[0,0,1]
	v_pk_fma_f32 v[146:147], v[132:133], v[146:147], v[150:151]
.LBB0_208:
	v_cndmask_b32_e64 v128, 0, 1, s[62:63]
	v_cmp_ne_u32_e64 s[2:3], 1, v128
	s_andn2_b64 vcc, exec, s[62:63]
	v_mov_b32_e32 v150, v88
	v_mov_b32_e32 v151, v89
	v_mov_b32_e32 v152, v90
	v_mov_b32_e32 v153, v91
	v_mov_b32_e32 v158, v92
	v_mov_b32_e32 v159, v93
	v_mov_b32_e32 v128, v94
	v_mov_b32_e32 v129, v95
	v_mov_b32_e32 v154, v80
	v_mov_b32_e32 v155, v81
	v_mov_b32_e32 v156, v82
	v_mov_b32_e32 v157, v83
	v_mov_b32_e32 v160, v84
	v_mov_b32_e32 v161, v85
	v_mov_b32_e32 v130, v86
	v_mov_b32_e32 v131, v87
	s_cbranch_vccnz .LBB0_210
	global_load_dwordx4 v[128:131], v[196:197], off offset:16
	global_load_dwordx4 v[150:153], v[196:197], off
	v_mov_b32_e32 v154, v88
	v_mov_b32_e32 v155, v81
	v_mov_b32_e32 v156, v80
	v_mov_b32_e32 v157, v89
	v_mov_b32_e32 v166, v92
	v_mov_b32_e32 v167, v85
	v_mov_b32_e32 v164, v84
	v_mov_b32_e32 v165, v93
	s_waitcnt vmcnt(1)
	v_mov_b32_e32 v112, v128
	v_mov_b32_e32 v113, v129
	v_mov_b32_e32 v114, v130
	v_mov_b32_e32 v115, v131
	v_mov_b32_e32 v158, v129
	s_waitcnt vmcnt(0)
	v_mov_b32_e32 v116, v150
	v_mov_b32_e32 v117, v151
	v_mov_b32_e32 v118, v152
	v_mov_b32_e32 v119, v153
	v_mov_b32_e32 v160, v150
	v_mov_b32_e32 v161, v153
	v_pk_mul_f32 v[160:161], v[154:155], v[160:161]
	v_mov_b32_e32 v154, v151
	v_mov_b32_e32 v155, v153
	v_mov_b32_e32 v132, v151
	v_mov_b32_e32 v133, v152
	v_pk_mul_f32 v[154:155], v[88:89], v[154:155]
	v_mov_b32_e32 v151, v152
	v_pk_fma_f32 v[154:155], v[80:81], v[150:151], v[154:155] neg_lo:[0,0,1] neg_hi:[0,0,1]
	v_pk_fma_f32 v[150:151], v[156:157], v[132:133], v[160:161]
	v_mov_b32_e32 v152, v90
	v_mov_b32_e32 v153, v83
	v_mov_b32_e32 v156, v128
	v_mov_b32_e32 v157, v131
	v_pk_mul_f32 v[152:153], v[152:153], v[156:157]
	v_mov_b32_e32 v156, v129
	v_mov_b32_e32 v159, v130
	v_mov_b32_e32 v132, v82
	v_mov_b32_e32 v133, v91
	v_pk_mul_f32 v[156:157], v[90:91], v[156:157]
	v_mov_b32_e32 v129, v130
	v_pk_fma_f32 v[156:157], v[82:83], v[128:129], v[156:157] neg_lo:[0,0,1] neg_hi:[0,0,1]
	v_pk_fma_f32 v[152:153], v[132:133], v[158:159], v[152:153]
	global_load_dwordx4 v[128:131], v[196:197], off offset:80
	global_load_dwordx4 v[158:161], v[196:197], off offset:64
	s_waitcnt vmcnt(1)
	v_mov_b32_e32 v120, v128
	v_mov_b32_e32 v121, v129
	v_mov_b32_e32 v122, v130
	v_mov_b32_e32 v123, v131
	v_mov_b32_e32 v162, v129
	s_waitcnt vmcnt(0)
	v_mov_b32_e32 v124, v158
	v_mov_b32_e32 v125, v159
	v_mov_b32_e32 v126, v160
	v_mov_b32_e32 v127, v161
	v_mov_b32_e32 v168, v158
	v_mov_b32_e32 v169, v161
	v_pk_mul_f32 v[166:167], v[166:167], v[168:169]
	v_mov_b32_e32 v168, v159
	v_mov_b32_e32 v132, v159
	v_mov_b32_e32 v133, v160
	v_pk_mul_f32 v[168:169], v[92:93], v[168:169]
	v_mov_b32_e32 v159, v160
	v_pk_fma_f32 v[160:161], v[84:85], v[158:159], v[168:169] neg_lo:[0,0,1] neg_hi:[0,0,1]
	v_pk_fma_f32 v[158:159], v[164:165], v[132:133], v[166:167]
	v_mov_b32_e32 v164, v94
	v_mov_b32_e32 v165, v87
	v_mov_b32_e32 v166, v128
	v_mov_b32_e32 v167, v131
	v_pk_mul_f32 v[164:165], v[164:165], v[166:167]
	v_mov_b32_e32 v166, v129
	v_mov_b32_e32 v163, v130
	v_mov_b32_e32 v132, v86
	v_mov_b32_e32 v133, v95
	v_pk_mul_f32 v[166:167], v[94:95], v[166:167]
	v_mov_b32_e32 v129, v130
	v_pk_fma_f32 v[130:131], v[86:87], v[128:129], v[166:167] neg_lo:[0,0,1] neg_hi:[0,0,1]
	v_pk_fma_f32 v[128:129], v[132:133], v[162:163], v[164:165]
.LBB0_210:
	s_and_b32 s61, s59, 0x380
	s_cmpk_lt_u32 s59, 0x400
	s_cselect_b64 vcc, -1, 0
	v_cndmask_b32_e32 v132, 1.0, v219, vcc
	v_pk_mul_f32 v[138:139], v[132:133], v[138:139] op_sel_hi:[0,1]
	v_pk_mul_f32 v[140:141], v[132:133], v[140:141] op_sel_hi:[0,1]
	v_pk_mul_f32 v[134:135], v[132:133], v[134:135] op_sel_hi:[0,1]
	v_pk_mul_f32 v[136:137], v[132:133], v[136:137] op_sel_hi:[0,1]
	v_readlane_b32 s80, v239, 32
	v_cvt_pk_bf16_f32 v138, v138, v139
	v_cvt_pk_bf16_f32 v139, v140, v141
	v_pk_mul_f32 v[140:141], v[132:133], v[144:145] op_sel_hi:[0,1]
	v_pk_mul_f32 v[144:145], v[132:133], v[148:149] op_sel_hi:[0,1]
	v_cvt_pk_bf16_f32 v134, v134, v135
	v_cvt_pk_bf16_f32 v135, v136, v137
	v_pk_mul_f32 v[136:137], v[132:133], v[142:143] op_sel_hi:[0,1]
	v_pk_mul_f32 v[142:143], v[132:133], v[146:147] op_sel_hi:[0,1]
	s_and_b64 s[62:63], vcc, exec
	v_readlane_b32 s82, v239, 34
	v_readlane_b32 s83, v239, 35
	v_readlane_b32 s84, v239, 36
	v_readlane_b32 s85, v239, 37
	v_cvt_pk_bf16_f32 v140, v140, v141
	v_cvt_pk_bf16_f32 v141, v144, v145
	v_cvt_pk_bf16_f32 v136, v136, v137
	v_cvt_pk_bf16_f32 v137, v142, v143
	s_cselect_b32 vcc_lo, s83, s85
	s_cselect_b32 vcc_hi, s82, s84
	s_mul_i32 s62, s60, 0x900
	s_ashr_i32 s52, s58, 31
	v_pk_mul_f32 v[142:143], v[132:133], v[154:155] op_sel_hi:[0,1]
	v_pk_mul_f32 v[144:145], v[132:133], v[156:157] op_sel_hi:[0,1]
	s_mul_hi_i32 s63, s60, 0x900
	s_add_u32 s62, s62, s58
	v_cvt_pk_bf16_f32 v142, v142, v143
	v_cvt_pk_bf16_f32 v143, v144, v145
	v_pk_mul_f32 v[144:145], v[132:133], v[160:161] op_sel_hi:[0,1]
	v_pk_mul_f32 v[130:131], v[132:133], v[130:131] op_sel_hi:[0,1]
	s_addc_u32 s63, s63, s52
	v_cvt_pk_bf16_f32 v144, v144, v145
	v_cvt_pk_bf16_f32 v145, v130, v131
	v_pk_mul_f32 v[130:131], v[132:133], v[150:151] op_sel_hi:[0,1]
	v_pk_mul_f32 v[146:147], v[132:133], v[152:153] op_sel_hi:[0,1]
	s_lshl_b64 s[62:63], s[62:63], 11
	v_cvt_pk_bf16_f32 v130, v130, v131
	v_cvt_pk_bf16_f32 v131, v146, v147
	v_pk_mul_f32 v[146:147], v[132:133], v[158:159] op_sel_hi:[0,1]
	v_pk_mul_f32 v[128:129], v[132:133], v[128:129] op_sel_hi:[0,1]
	s_add_u32 s52, vcc_hi, s62
	v_cvt_pk_bf16_f32 v146, v146, v147
	v_cvt_pk_bf16_f32 v147, v128, v129
	ds_write2_b64 v220, v[138:139], v[140:141] offset1:2
	ds_write2_b64 v220, v[134:135], v[136:137] offset0:4 offset1:6
	ds_write2_b64 v220, v[142:143], v[144:145] offset0:8 offset1:10
	ds_write2_b64 v220, v[130:131], v[146:147] offset0:12 offset1:14
	s_addc_u32 s63, vcc_lo, s63
	s_lshl_b32 s61, s61, 1
	ds_read2_b64 v[128:131], v221 offset1:1
	ds_read2_b64 v[140:143], v222 offset1:1
	s_add_u32 s62, s52, s61
	s_addc_u32 s63, s63, 0
	v_lshl_add_u64 v[134:135], s[62:63], 0, v[178:179]
	v_lshl_add_u64 v[136:137], v[134:135], 0, v[186:187]
	s_waitcnt lgkmcnt(1)
	global_store_dwordx4 v[136:137], v[128:131], off
	ds_read2_b64 v[128:131], v223 offset1:1
	ds_read2_b64 v[144:147], v224 offset1:1
	v_lshl_add_u64 v[138:139], v[134:135], 0, v[188:189]
	s_waitcnt lgkmcnt(2)
	global_store_dwordx4 v[138:139], v[140:143], off
	v_readlane_b32 s81, v239, 33
	v_readlane_b32 s86, v239, 38
	v_lshl_add_u64 v[140:141], v[134:135], 0, v[190:191]
	v_lshl_add_u64 v[142:143], v[134:135], 0, v[192:193]
	v_readlane_b32 s87, v239, 39
	s_waitcnt lgkmcnt(1)
	global_store_dwordx4 v[140:141], v[128:131], off
	s_waitcnt lgkmcnt(0)
	global_store_dwordx4 v[142:143], v[144:147], off
	s_and_b64 vcc, exec, s[2:3]
	s_nop 0
	v_mov_b32_e32 v144, v56
	v_mov_b32_e32 v145, v57
	v_mov_b32_e32 v146, v58
	v_mov_b32_e32 v147, v59
	v_mov_b32_e32 v152, v60
	v_mov_b32_e32 v153, v61
	v_mov_b32_e32 v156, v62
	v_mov_b32_e32 v157, v63
	v_mov_b32_e32 v148, v48
	v_mov_b32_e32 v149, v49
	v_mov_b32_e32 v150, v50
	v_mov_b32_e32 v151, v51
	v_mov_b32_e32 v154, v52
	v_mov_b32_e32 v155, v53
	v_mov_b32_e32 v158, v54
	v_mov_b32_e32 v159, v55
	s_cbranch_vccnz .LBB0_212
	v_lshl_add_u64 v[152:153], s[22:23], 3, v[194:195]
	v_mov_b32_e32 v128, v240
	v_mov_b32_e32 v129, v241
	v_mov_b32_e32 v130, v242
	v_mov_b32_e32 v131, v243
	v_mov_b32_e32 v144, v244
	v_mov_b32_e32 v145, v245
	v_mov_b32_e32 v146, v246
	v_mov_b32_e32 v147, v247
	v_mov_b32_e32 v148, v56
	v_mov_b32_e32 v149, v49
	v_mov_b32_e32 v156, v48
	v_mov_b32_e32 v157, v57
	v_mov_b32_e32 v162, v60
	v_mov_b32_e32 v163, v53
	v_mov_b32_e32 v154, v129
	v_mov_b32_e32 v158, v144
	v_mov_b32_e32 v159, v147
	v_pk_mul_f32 v[158:159], v[148:149], v[158:159]
	v_mov_b32_e32 v148, v145
	v_mov_b32_e32 v149, v147
	v_mov_b32_e32 v150, v145
	v_mov_b32_e32 v151, v146
	v_pk_mul_f32 v[148:149], v[56:57], v[148:149]
	v_mov_b32_e32 v145, v146
	v_pk_fma_f32 v[148:149], v[48:49], v[144:145], v[148:149] neg_lo:[0,0,1] neg_hi:[0,0,1]
	v_pk_fma_f32 v[144:145], v[156:157], v[150:151], v[158:159]
	v_mov_b32_e32 v150, v58
	v_mov_b32_e32 v151, v51
	v_mov_b32_e32 v156, v128
	v_mov_b32_e32 v157, v131
	v_pk_mul_f32 v[156:157], v[150:151], v[156:157]
	v_mov_b32_e32 v150, v129
	v_mov_b32_e32 v151, v131
	v_mov_b32_e32 v155, v130
	v_mov_b32_e32 v146, v50
	v_mov_b32_e32 v147, v59
	v_pk_mul_f32 v[150:151], v[58:59], v[150:151]
	v_mov_b32_e32 v129, v130
	v_pk_fma_f32 v[150:151], v[50:51], v[128:129], v[150:151] neg_lo:[0,0,1] neg_hi:[0,0,1]
	v_pk_fma_f32 v[146:147], v[146:147], v[154:155], v[156:157]
	v_mov_b32_e32 v128, v248
	v_mov_b32_e32 v129, v249
	v_mov_b32_e32 v130, v250
	v_mov_b32_e32 v131, v251
	s_nop 0
	v_mov_b32_e32 v152, v252
	v_mov_b32_e32 v153, v253
	v_mov_b32_e32 v154, v254
	v_mov_b32_e32 v155, v255
	v_mov_b32_e32 v158, v52
	v_mov_b32_e32 v159, v61
	v_mov_b32_e32 v160, v129
	v_mov_b32_e32 v164, v152
	v_mov_b32_e32 v165, v155
	v_pk_mul_f32 v[162:163], v[162:163], v[164:165]
	v_mov_b32_e32 v164, v153
	v_mov_b32_e32 v156, v153
	v_mov_b32_e32 v157, v154
	v_pk_mul_f32 v[164:165], v[60:61], v[164:165]
	v_mov_b32_e32 v153, v154
	v_pk_fma_f32 v[154:155], v[52:53], v[152:153], v[164:165] neg_lo:[0,0,1] neg_hi:[0,0,1]
	v_pk_fma_f32 v[152:153], v[158:159], v[156:157], v[162:163]
	v_mov_b32_e32 v158, v62
	v_mov_b32_e32 v159, v55
	v_mov_b32_e32 v162, v128
	v_mov_b32_e32 v163, v131
	v_pk_mul_f32 v[162:163], v[158:159], v[162:163]
	v_mov_b32_e32 v158, v129
	v_mov_b32_e32 v159, v131
	v_mov_b32_e32 v161, v130
	v_mov_b32_e32 v156, v54
	v_mov_b32_e32 v157, v63
	v_pk_mul_f32 v[158:159], v[62:63], v[158:159]
	v_mov_b32_e32 v129, v130
	v_pk_fma_f32 v[158:159], v[54:55], v[128:129], v[158:159] neg_lo:[0,0,1] neg_hi:[0,0,1]
	v_pk_fma_f32 v[156:157], v[156:157], v[160:161], v[162:163]
.LBB0_212:
	s_and_b64 vcc, exec, s[2:3]
	v_mov_b32_e32 v160, v24
	v_mov_b32_e32 v161, v25
	v_mov_b32_e32 v162, v26
	v_mov_b32_e32 v163, v27
	v_mov_b32_e32 v168, v28
	v_mov_b32_e32 v169, v29
	v_mov_b32_e32 v128, v30
	v_mov_b32_e32 v129, v31
	v_mov_b32_e32 v164, v16
	v_mov_b32_e32 v165, v17
	v_mov_b32_e32 v166, v18
	v_mov_b32_e32 v167, v19
	v_mov_b32_e32 v170, v20
	v_mov_b32_e32 v171, v21
	v_mov_b32_e32 v130, v22
	v_mov_b32_e32 v131, v23
	s_cbranch_vccnz .LBB0_214
	v_mov_b32_e32 v128, v112
	v_mov_b32_e32 v129, v113
	v_mov_b32_e32 v130, v114
	v_mov_b32_e32 v131, v115
	v_mov_b32_e32 v160, v116
	v_mov_b32_e32 v161, v117
	v_mov_b32_e32 v162, v118
	v_mov_b32_e32 v163, v119
	v_mov_b32_e32 v164, v24
	v_mov_b32_e32 v165, v17
	v_mov_b32_e32 v170, v16
	v_mov_b32_e32 v171, v25
	v_mov_b32_e32 v228, v28
	v_mov_b32_e32 v229, v21
	v_mov_b32_e32 v226, v20
	v_mov_b32_e32 v227, v29
	v_mov_b32_e32 v168, v129
	v_mov_b32_e32 v172, v160
	v_mov_b32_e32 v173, v163
	v_pk_mul_f32 v[172:173], v[164:165], v[172:173]
	v_mov_b32_e32 v164, v161
	v_mov_b32_e32 v165, v163
	v_mov_b32_e32 v166, v161
	v_mov_b32_e32 v167, v162
	v_pk_mul_f32 v[164:165], v[24:25], v[164:165]
	v_mov_b32_e32 v161, v162
	v_pk_fma_f32 v[164:165], v[16:17], v[160:161], v[164:165] neg_lo:[0,0,1] neg_hi:[0,0,1]
	v_pk_fma_f32 v[160:161], v[170:171], v[166:167], v[172:173]
	v_mov_b32_e32 v166, v26
	v_mov_b32_e32 v167, v19
	v_mov_b32_e32 v170, v128
	v_mov_b32_e32 v171, v131
	v_pk_mul_f32 v[170:171], v[166:167], v[170:171]
	v_mov_b32_e32 v166, v129
	v_mov_b32_e32 v167, v131
	v_mov_b32_e32 v169, v130
	v_mov_b32_e32 v162, v18
	v_mov_b32_e32 v163, v27
	v_pk_mul_f32 v[166:167], v[26:27], v[166:167]
	v_mov_b32_e32 v129, v130
	v_pk_fma_f32 v[166:167], v[18:19], v[128:129], v[166:167] neg_lo:[0,0,1] neg_hi:[0,0,1]
	v_pk_fma_f32 v[162:163], v[162:163], v[168:169], v[170:171]
	v_mov_b32_e32 v128, v120
	v_mov_b32_e32 v129, v121
	v_mov_b32_e32 v130, v122
	v_mov_b32_e32 v131, v123
	v_mov_b32_e32 v168, v124
	v_mov_b32_e32 v169, v125
	v_mov_b32_e32 v170, v126
	v_mov_b32_e32 v171, v127
	v_mov_b32_e32 v174, v129
	v_mov_b32_e32 v230, v168
	v_mov_b32_e32 v231, v171
	v_pk_mul_f32 v[228:229], v[228:229], v[230:231]
	v_mov_b32_e32 v230, v169
	v_mov_b32_e32 v172, v169
	v_mov_b32_e32 v173, v170
	v_pk_mul_f32 v[230:231], v[28:29], v[230:231]
	v_mov_b32_e32 v169, v170
	v_pk_fma_f32 v[170:171], v[20:21], v[168:169], v[230:231] neg_lo:[0,0,1] neg_hi:[0,0,1]
	v_pk_fma_f32 v[168:169], v[226:227], v[172:173], v[228:229]
	v_mov_b32_e32 v226, v30
	v_mov_b32_e32 v227, v23
	v_mov_b32_e32 v228, v128
	v_mov_b32_e32 v229, v131
	v_pk_mul_f32 v[226:227], v[226:227], v[228:229]
	v_mov_b32_e32 v228, v129
	v_mov_b32_e32 v175, v130
	v_mov_b32_e32 v172, v22
	v_mov_b32_e32 v173, v31
	v_pk_mul_f32 v[228:229], v[30:31], v[228:229]
	v_mov_b32_e32 v129, v130
	v_pk_fma_f32 v[130:131], v[22:23], v[128:129], v[228:229] neg_lo:[0,0,1] neg_hi:[0,0,1]
	v_pk_fma_f32 v[128:129], v[172:173], v[174:175], v[226:227]
.LBB0_214:
	v_mov_b32_e32 v133, v132
	v_pk_mul_f32 v[148:149], v[132:133], v[148:149]
	v_pk_mul_f32 v[150:151], v[132:133], v[150:151]
	v_pk_mul_f32 v[144:145], v[132:133], v[144:145]
	v_pk_mul_f32 v[146:147], v[132:133], v[146:147]
	v_cvt_pk_bf16_f32 v148, v148, v149
	v_cvt_pk_bf16_f32 v149, v150, v151
	v_pk_mul_f32 v[150:151], v[132:133], v[154:155]
	v_pk_mul_f32 v[154:155], v[132:133], v[158:159]
	v_cvt_pk_bf16_f32 v144, v144, v145
	v_cvt_pk_bf16_f32 v145, v146, v147
	v_pk_mul_f32 v[146:147], v[132:133], v[152:153]
	v_pk_mul_f32 v[152:153], v[132:133], v[156:157]
	v_cvt_pk_bf16_f32 v150, v150, v151
	v_cvt_pk_bf16_f32 v151, v154, v155
	v_cvt_pk_bf16_f32 v146, v146, v147
	v_cvt_pk_bf16_f32 v147, v152, v153
	v_pk_mul_f32 v[152:153], v[132:133], v[164:165]
	v_pk_mul_f32 v[154:155], v[132:133], v[166:167]
	v_cvt_pk_bf16_f32 v152, v152, v153
	v_cvt_pk_bf16_f32 v153, v154, v155
	v_pk_mul_f32 v[154:155], v[132:133], v[170:171]
	v_pk_mul_f32 v[130:131], v[132:133], v[130:131]
	v_cvt_pk_bf16_f32 v154, v154, v155
	v_cvt_pk_bf16_f32 v155, v130, v131
	v_pk_mul_f32 v[130:131], v[132:133], v[160:161]
	v_pk_mul_f32 v[156:157], v[132:133], v[162:163]
	v_cvt_pk_bf16_f32 v130, v130, v131
	v_cvt_pk_bf16_f32 v131, v156, v157
	v_pk_mul_f32 v[156:157], v[132:133], v[168:169]
	v_pk_mul_f32 v[128:129], v[132:133], v[128:129]
	v_cvt_pk_bf16_f32 v156, v156, v157
	v_cvt_pk_bf16_f32 v157, v128, v129
	ds_write2_b64 v220, v[148:149], v[150:151] offset1:2
	ds_write2_b64 v220, v[144:145], v[146:147] offset0:4 offset1:6
	ds_write2_b64 v220, v[152:153], v[154:155] offset0:8 offset1:10
	ds_write2_b64 v220, v[130:131], v[156:157] offset0:12 offset1:14
	ds_read2_b64 v[128:131], v221 offset1:1
	ds_read2_b64 v[144:147], v222 offset1:1
	ds_read2_b64 v[148:151], v223 offset1:1
	ds_read2_b64 v[152:155], v224 offset1:1
	s_waitcnt lgkmcnt(3)
	global_store_dwordx4 v[136:137], v[128:131], off offset:128
	s_waitcnt lgkmcnt(2)
	global_store_dwordx4 v[138:139], v[144:147], off offset:128
	s_waitcnt lgkmcnt(1)
	global_store_dwordx4 v[140:141], v[148:151], off offset:128
	s_waitcnt lgkmcnt(0)
	global_store_dwordx4 v[142:143], v[152:155], off offset:128
	s_and_b64 vcc, exec, s[2:3]
	v_mov_b32_e32 v136, v104
	v_mov_b32_e32 v137, v105
	v_mov_b32_e32 v138, v106
	v_mov_b32_e32 v139, v107
	v_mov_b32_e32 v144, v108
	v_mov_b32_e32 v145, v109
	v_mov_b32_e32 v148, v110
	v_mov_b32_e32 v149, v111
	v_mov_b32_e32 v140, v96
	v_mov_b32_e32 v141, v97
	v_mov_b32_e32 v142, v98
	v_mov_b32_e32 v143, v99
	v_mov_b32_e32 v146, v100
	v_mov_b32_e32 v147, v101
	v_mov_b32_e32 v150, v102
	v_mov_b32_e32 v151, v103
	s_cbranch_vccnz .LBB0_216
	v_lshl_add_u64 v[144:145], s[22:23], 3, v[194:195]
	v_mov_b32_e32 v128, v240
	v_mov_b32_e32 v129, v241
	v_mov_b32_e32 v130, v242
	v_mov_b32_e32 v131, v243
	v_mov_b32_e32 v136, v244
	v_mov_b32_e32 v137, v245
	v_mov_b32_e32 v138, v246
	v_mov_b32_e32 v139, v247
	v_mov_b32_e32 v140, v104
	v_mov_b32_e32 v141, v97
	v_mov_b32_e32 v148, v96
	v_mov_b32_e32 v149, v105
	v_mov_b32_e32 v154, v108
	v_mov_b32_e32 v155, v101
	v_mov_b32_e32 v146, v129
	v_mov_b32_e32 v150, v136
	v_mov_b32_e32 v151, v139
	v_pk_mul_f32 v[150:151], v[140:141], v[150:151]
	v_mov_b32_e32 v140, v137
	v_mov_b32_e32 v141, v139
	v_mov_b32_e32 v142, v137
	v_mov_b32_e32 v143, v138
	v_pk_mul_f32 v[140:141], v[104:105], v[140:141]
	v_mov_b32_e32 v137, v138
	v_pk_fma_f32 v[140:141], v[96:97], v[136:137], v[140:141] neg_lo:[0,0,1] neg_hi:[0,0,1]
	v_pk_fma_f32 v[136:137], v[148:149], v[142:143], v[150:151]
	v_mov_b32_e32 v142, v106
	v_mov_b32_e32 v143, v99
	v_mov_b32_e32 v148, v128
	v_mov_b32_e32 v149, v131
	v_pk_mul_f32 v[148:149], v[142:143], v[148:149]
	v_mov_b32_e32 v142, v129
	v_mov_b32_e32 v143, v131
	v_mov_b32_e32 v147, v130
	v_mov_b32_e32 v138, v98
	v_mov_b32_e32 v139, v107
	v_pk_mul_f32 v[142:143], v[106:107], v[142:143]
	v_mov_b32_e32 v129, v130
	v_pk_fma_f32 v[142:143], v[98:99], v[128:129], v[142:143] neg_lo:[0,0,1] neg_hi:[0,0,1]
	v_pk_fma_f32 v[138:139], v[138:139], v[146:147], v[148:149]
	v_mov_b32_e32 v128, v248
	v_mov_b32_e32 v129, v249
	v_mov_b32_e32 v130, v250
	v_mov_b32_e32 v131, v251
	s_nop 0
	v_mov_b32_e32 v144, v252
	v_mov_b32_e32 v145, v253
	v_mov_b32_e32 v146, v254
	v_mov_b32_e32 v147, v255
	v_mov_b32_e32 v150, v100
	v_mov_b32_e32 v151, v109
	v_mov_b32_e32 v152, v129
	v_mov_b32_e32 v156, v144
	v_mov_b32_e32 v157, v147
	v_pk_mul_f32 v[154:155], v[154:155], v[156:157]
	v_mov_b32_e32 v156, v145
	v_mov_b32_e32 v148, v145
	v_mov_b32_e32 v149, v146
	v_pk_mul_f32 v[156:157], v[108:109], v[156:157]
	v_mov_b32_e32 v145, v146
	v_pk_fma_f32 v[146:147], v[100:101], v[144:145], v[156:157] neg_lo:[0,0,1] neg_hi:[0,0,1]
	v_pk_fma_f32 v[144:145], v[150:151], v[148:149], v[154:155]
	v_mov_b32_e32 v150, v110
	v_mov_b32_e32 v151, v103
	v_mov_b32_e32 v154, v128
	v_mov_b32_e32 v155, v131
	v_pk_mul_f32 v[154:155], v[150:151], v[154:155]
	v_mov_b32_e32 v150, v129
	v_mov_b32_e32 v151, v131
	v_mov_b32_e32 v153, v130
	v_mov_b32_e32 v148, v102
	v_mov_b32_e32 v149, v111
	v_pk_mul_f32 v[150:151], v[110:111], v[150:151]
	v_mov_b32_e32 v129, v130
	v_pk_fma_f32 v[150:151], v[102:103], v[128:129], v[150:151] neg_lo:[0,0,1] neg_hi:[0,0,1]
	v_pk_fma_f32 v[148:149], v[148:149], v[152:153], v[154:155]
.LBB0_216:
	s_and_b64 vcc, exec, s[2:3]
	v_mov_b32_e32 v152, v72
	v_mov_b32_e32 v153, v73
	v_mov_b32_e32 v154, v74
	v_mov_b32_e32 v155, v75
	v_mov_b32_e32 v160, v76
	v_mov_b32_e32 v161, v77
	v_mov_b32_e32 v128, v78
	v_mov_b32_e32 v129, v79
	v_mov_b32_e32 v156, v64
	v_mov_b32_e32 v157, v65
	v_mov_b32_e32 v158, v66
	v_mov_b32_e32 v159, v67
	v_mov_b32_e32 v162, v68
	v_mov_b32_e32 v163, v69
	v_mov_b32_e32 v130, v70
	v_mov_b32_e32 v131, v71
	s_cbranch_vccnz .LBB0_218
	global_load_dwordx4 v[128:131], v[198:199], off offset:16
	global_load_dwordx4 v[152:155], v[198:199], off
	v_mov_b32_e32 v156, v72
	v_mov_b32_e32 v157, v65
	v_mov_b32_e32 v162, v64
	v_mov_b32_e32 v163, v73
	v_mov_b32_e32 v170, v76
	v_mov_b32_e32 v171, v69
	v_mov_b32_e32 v168, v68
	v_mov_b32_e32 v169, v77
	s_waitcnt vmcnt(1)
	v_mov_b32_e32 v96, v128
	v_mov_b32_e32 v97, v129
	v_mov_b32_e32 v98, v130
	v_mov_b32_e32 v99, v131
	v_mov_b32_e32 v160, v129
	s_waitcnt vmcnt(0)
	v_mov_b32_e32 v100, v152
	v_mov_b32_e32 v101, v153
	v_mov_b32_e32 v102, v154
	v_mov_b32_e32 v103, v155
	v_mov_b32_e32 v164, v152
	v_mov_b32_e32 v165, v155
	v_pk_mul_f32 v[164:165], v[156:157], v[164:165]
	v_mov_b32_e32 v156, v153
	v_mov_b32_e32 v157, v155
	v_mov_b32_e32 v158, v153
	v_mov_b32_e32 v159, v154
	v_pk_mul_f32 v[156:157], v[72:73], v[156:157]
	v_mov_b32_e32 v153, v154
	v_pk_fma_f32 v[156:157], v[64:65], v[152:153], v[156:157] neg_lo:[0,0,1] neg_hi:[0,0,1]
	v_pk_fma_f32 v[152:153], v[162:163], v[158:159], v[164:165]
	v_mov_b32_e32 v158, v74
	v_mov_b32_e32 v159, v67
	v_mov_b32_e32 v162, v128
	v_mov_b32_e32 v163, v131
	v_pk_mul_f32 v[162:163], v[158:159], v[162:163]
	v_mov_b32_e32 v158, v129
	v_mov_b32_e32 v159, v131
	v_mov_b32_e32 v161, v130
	v_mov_b32_e32 v154, v66
	v_mov_b32_e32 v155, v75
	v_pk_mul_f32 v[158:159], v[74:75], v[158:159]
	v_mov_b32_e32 v129, v130
	v_pk_fma_f32 v[158:159], v[66:67], v[128:129], v[158:159] neg_lo:[0,0,1] neg_hi:[0,0,1]
	v_pk_fma_f32 v[154:155], v[154:155], v[160:161], v[162:163]
	global_load_dwordx4 v[128:131], v[198:199], off offset:80
	global_load_dwordx4 v[160:163], v[198:199], off offset:64
	s_waitcnt vmcnt(1)
	v_mov_b32_e32 v104, v128
	v_mov_b32_e32 v105, v129
	v_mov_b32_e32 v106, v130
	v_mov_b32_e32 v107, v131
	v_mov_b32_e32 v166, v129
	s_waitcnt vmcnt(0)
	v_mov_b32_e32 v108, v160
	v_mov_b32_e32 v109, v161
	v_mov_b32_e32 v110, v162
	v_mov_b32_e32 v111, v163
	v_mov_b32_e32 v172, v160
	v_mov_b32_e32 v173, v163
	v_pk_mul_f32 v[170:171], v[170:171], v[172:173]
	v_mov_b32_e32 v172, v161
	v_mov_b32_e32 v164, v161
	v_mov_b32_e32 v165, v162
	v_pk_mul_f32 v[172:173], v[76:77], v[172:173]
	v_mov_b32_e32 v161, v162
	v_pk_fma_f32 v[162:163], v[68:69], v[160:161], v[172:173] neg_lo:[0,0,1] neg_hi:[0,0,1]
	v_pk_fma_f32 v[160:161], v[168:169], v[164:165], v[170:171]
	v_mov_b32_e32 v168, v78
	v_mov_b32_e32 v169, v71
	v_mov_b32_e32 v170, v128
	v_mov_b32_e32 v171, v131
	v_pk_mul_f32 v[168:169], v[168:169], v[170:171]
	v_mov_b32_e32 v170, v129
	v_mov_b32_e32 v167, v130
	v_mov_b32_e32 v164, v70
	v_mov_b32_e32 v165, v79
	v_pk_mul_f32 v[170:171], v[78:79], v[170:171]
	v_mov_b32_e32 v129, v130
	v_pk_fma_f32 v[130:131], v[70:71], v[128:129], v[170:171] neg_lo:[0,0,1] neg_hi:[0,0,1]
	v_pk_fma_f32 v[128:129], v[164:165], v[166:167], v[168:169]
.LBB0_218:
	v_pk_mul_f32 v[140:141], v[132:133], v[140:141]
	v_pk_mul_f32 v[142:143], v[132:133], v[142:143]
	v_pk_mul_f32 v[136:137], v[132:133], v[136:137]
	v_pk_mul_f32 v[138:139], v[132:133], v[138:139]
	v_cvt_pk_bf16_f32 v140, v140, v141
	v_cvt_pk_bf16_f32 v141, v142, v143
	v_pk_mul_f32 v[142:143], v[132:133], v[146:147]
	v_pk_mul_f32 v[146:147], v[132:133], v[150:151]
	v_cvt_pk_bf16_f32 v136, v136, v137
	v_cvt_pk_bf16_f32 v137, v138, v139
	v_pk_mul_f32 v[138:139], v[132:133], v[144:145]
	v_pk_mul_f32 v[144:145], v[132:133], v[148:149]
	v_cvt_pk_bf16_f32 v142, v142, v143
	v_cvt_pk_bf16_f32 v143, v146, v147
	v_cvt_pk_bf16_f32 v138, v138, v139
	v_cvt_pk_bf16_f32 v139, v144, v145
	v_pk_mul_f32 v[144:145], v[132:133], v[156:157]
	v_pk_mul_f32 v[146:147], v[132:133], v[158:159]
	v_cvt_pk_bf16_f32 v144, v144, v145
	v_cvt_pk_bf16_f32 v145, v146, v147
	v_pk_mul_f32 v[146:147], v[132:133], v[162:163]
	v_pk_mul_f32 v[130:131], v[132:133], v[130:131]
	v_cvt_pk_bf16_f32 v146, v146, v147
	v_cvt_pk_bf16_f32 v147, v130, v131
	v_pk_mul_f32 v[130:131], v[132:133], v[152:153]
	v_pk_mul_f32 v[148:149], v[132:133], v[154:155]
	v_cvt_pk_bf16_f32 v130, v130, v131
	v_cvt_pk_bf16_f32 v131, v148, v149
	v_pk_mul_f32 v[148:149], v[132:133], v[160:161]
	v_pk_mul_f32 v[128:129], v[132:133], v[128:129]
	v_cvt_pk_bf16_f32 v148, v148, v149
	v_cvt_pk_bf16_f32 v149, v128, v129
	ds_write2_b64 v220, v[140:141], v[142:143] offset1:2
	ds_write2_b64 v220, v[136:137], v[138:139] offset0:4 offset1:6
	ds_write2_b64 v220, v[144:145], v[146:147] offset0:8 offset1:10
	ds_write2_b64 v220, v[130:131], v[148:149] offset0:12 offset1:14
	ds_read2_b64 v[128:131], v221 offset1:1
	ds_read2_b64 v[136:139], v222 offset1:1
	s_mov_b64 s[62:63], 0x10000
	v_lshl_add_u64 v[144:145], v[134:135], 0, s[62:63]
	v_lshl_add_u64 v[140:141], v[144:145], 0, v[186:187]
	s_waitcnt lgkmcnt(1)
	global_store_dwordx4 v[140:141], v[128:131], off
	ds_read2_b64 v[128:131], v223 offset1:1
	ds_read2_b64 v[140:143], v224 offset1:1
	v_lshl_add_u64 v[146:147], v[144:145], 0, v[188:189]
	s_waitcnt lgkmcnt(2)
	global_store_dwordx4 v[146:147], v[136:139], off
	s_nop 1
	v_lshl_add_u64 v[136:137], v[144:145], 0, v[190:191]
	s_waitcnt lgkmcnt(1)
	global_store_dwordx4 v[136:137], v[128:131], off
	s_nop 1
	v_lshl_add_u64 v[128:129], v[144:145], 0, v[192:193]
	s_waitcnt lgkmcnt(0)
	global_store_dwordx4 v[128:129], v[140:143], off
	s_and_b64 vcc, exec, s[2:3]
	v_mov_b32_e32 v136, v40
	v_mov_b32_e32 v137, v41
	v_mov_b32_e32 v138, v42
	v_mov_b32_e32 v139, v43
	v_mov_b32_e32 v144, v44
	v_mov_b32_e32 v145, v45
	v_mov_b32_e32 v148, v46
	v_mov_b32_e32 v149, v47
	v_mov_b32_e32 v140, v32
	v_mov_b32_e32 v141, v33
	v_mov_b32_e32 v142, v34
	v_mov_b32_e32 v143, v35
	v_mov_b32_e32 v146, v36
	v_mov_b32_e32 v147, v37
	v_mov_b32_e32 v150, v38
	v_mov_b32_e32 v151, v39
	s_cbranch_vccnz .LBB0_220
	v_lshl_add_u64 v[144:145], s[22:23], 3, v[194:195]
	v_mov_b32_e32 v128, v240
	v_mov_b32_e32 v129, v241
	v_mov_b32_e32 v130, v242
	v_mov_b32_e32 v131, v243
	v_mov_b32_e32 v136, v244
	v_mov_b32_e32 v137, v245
	v_mov_b32_e32 v138, v246
	v_mov_b32_e32 v139, v247
	v_mov_b32_e32 v140, v40
	v_mov_b32_e32 v141, v33
	v_mov_b32_e32 v148, v32
	v_mov_b32_e32 v149, v41
	v_mov_b32_e32 v154, v44
	v_mov_b32_e32 v155, v37
	v_mov_b32_e32 v146, v129
	v_mov_b32_e32 v150, v136
	v_mov_b32_e32 v151, v139
	v_pk_mul_f32 v[150:151], v[140:141], v[150:151]
	v_mov_b32_e32 v140, v137
	v_mov_b32_e32 v141, v139
	v_mov_b32_e32 v142, v137
	v_mov_b32_e32 v143, v138
	v_pk_mul_f32 v[140:141], v[40:41], v[140:141]
	v_mov_b32_e32 v137, v138
	v_pk_fma_f32 v[140:141], v[32:33], v[136:137], v[140:141] neg_lo:[0,0,1] neg_hi:[0,0,1]
	v_pk_fma_f32 v[136:137], v[148:149], v[142:143], v[150:151]
	v_mov_b32_e32 v142, v42
	v_mov_b32_e32 v143, v35
	v_mov_b32_e32 v148, v128
	v_mov_b32_e32 v149, v131
	v_pk_mul_f32 v[148:149], v[142:143], v[148:149]
	v_mov_b32_e32 v142, v129
	v_mov_b32_e32 v143, v131
	v_mov_b32_e32 v147, v130
	v_mov_b32_e32 v138, v34
	v_mov_b32_e32 v139, v43
	v_pk_mul_f32 v[142:143], v[42:43], v[142:143]
	v_mov_b32_e32 v129, v130
	v_pk_fma_f32 v[142:143], v[34:35], v[128:129], v[142:143] neg_lo:[0,0,1] neg_hi:[0,0,1]
	v_pk_fma_f32 v[138:139], v[138:139], v[146:147], v[148:149]
	v_mov_b32_e32 v128, v248
	v_mov_b32_e32 v129, v249
	v_mov_b32_e32 v130, v250
	v_mov_b32_e32 v131, v251
	s_nop 0
	v_mov_b32_e32 v144, v252
	v_mov_b32_e32 v145, v253
	v_mov_b32_e32 v146, v254
	v_mov_b32_e32 v147, v255
	v_mov_b32_e32 v150, v36
	v_mov_b32_e32 v151, v45
	v_mov_b32_e32 v152, v129
	v_mov_b32_e32 v156, v144
	v_mov_b32_e32 v157, v147
	v_pk_mul_f32 v[154:155], v[154:155], v[156:157]
	v_mov_b32_e32 v156, v145
	v_mov_b32_e32 v148, v145
	v_mov_b32_e32 v149, v146
	v_pk_mul_f32 v[156:157], v[44:45], v[156:157]
	v_mov_b32_e32 v145, v146
	v_pk_fma_f32 v[146:147], v[36:37], v[144:145], v[156:157] neg_lo:[0,0,1] neg_hi:[0,0,1]
	v_pk_fma_f32 v[144:145], v[150:151], v[148:149], v[154:155]
	v_mov_b32_e32 v150, v46
	v_mov_b32_e32 v151, v39
	v_mov_b32_e32 v154, v128
	v_mov_b32_e32 v155, v131
	v_pk_mul_f32 v[154:155], v[150:151], v[154:155]
	v_mov_b32_e32 v150, v129
	v_mov_b32_e32 v151, v131
	v_mov_b32_e32 v153, v130
	v_mov_b32_e32 v148, v38
	v_mov_b32_e32 v149, v47
	v_pk_mul_f32 v[150:151], v[46:47], v[150:151]
	v_mov_b32_e32 v129, v130
	v_pk_fma_f32 v[150:151], v[38:39], v[128:129], v[150:151] neg_lo:[0,0,1] neg_hi:[0,0,1]
	v_pk_fma_f32 v[148:149], v[148:149], v[152:153], v[154:155]
.LBB0_220:
	s_and_b64 vcc, exec, s[2:3]
	v_mov_b32_e32 v152, v8
	v_mov_b32_e32 v153, v9
	v_mov_b32_e32 v154, v10
	v_mov_b32_e32 v155, v11
	v_mov_b32_e32 v160, v12
	v_mov_b32_e32 v161, v13
	v_mov_b32_e32 v128, v14
	v_mov_b32_e32 v129, v15
	v_mov_b32_e32 v156, v0
	v_mov_b32_e32 v157, v1
	v_mov_b32_e32 v158, v2
	v_mov_b32_e32 v159, v3
	v_mov_b32_e32 v162, v4
	v_mov_b32_e32 v163, v5
	v_mov_b32_e32 v130, v6
	v_mov_b32_e32 v131, v7
	v_readlane_b32 s62, v239, 60
	s_cbranch_vccnz .LBB0_222
	v_mov_b32_e32 v128, v96
	v_mov_b32_e32 v129, v97
	v_mov_b32_e32 v130, v98
	v_mov_b32_e32 v131, v99
	v_mov_b32_e32 v152, v100
	v_mov_b32_e32 v153, v101
	v_mov_b32_e32 v154, v102
	v_mov_b32_e32 v155, v103
	v_mov_b32_e32 v156, v8
	v_mov_b32_e32 v157, v1
	v_mov_b32_e32 v162, v0
	v_mov_b32_e32 v163, v9
	v_mov_b32_e32 v170, v12
	v_mov_b32_e32 v171, v5
	v_mov_b32_e32 v168, v4
	v_mov_b32_e32 v169, v13
	v_mov_b32_e32 v160, v129
	v_mov_b32_e32 v164, v152
	v_mov_b32_e32 v165, v155
	v_pk_mul_f32 v[164:165], v[156:157], v[164:165]
	v_mov_b32_e32 v156, v153
	v_mov_b32_e32 v157, v155
	v_mov_b32_e32 v158, v153
	v_mov_b32_e32 v159, v154
	v_pk_mul_f32 v[156:157], v[8:9], v[156:157]
	v_mov_b32_e32 v153, v154
	v_pk_fma_f32 v[156:157], v[0:1], v[152:153], v[156:157] neg_lo:[0,0,1] neg_hi:[0,0,1]
	v_pk_fma_f32 v[152:153], v[162:163], v[158:159], v[164:165]
	v_mov_b32_e32 v158, v10
	v_mov_b32_e32 v159, v3
	v_mov_b32_e32 v162, v128
	v_mov_b32_e32 v163, v131
	v_pk_mul_f32 v[162:163], v[158:159], v[162:163]
	v_mov_b32_e32 v158, v129
	v_mov_b32_e32 v159, v131
	v_mov_b32_e32 v161, v130
	v_mov_b32_e32 v154, v2
	v_mov_b32_e32 v155, v11
	v_pk_mul_f32 v[158:159], v[10:11], v[158:159]
	v_mov_b32_e32 v129, v130
	v_pk_fma_f32 v[158:159], v[2:3], v[128:129], v[158:159] neg_lo:[0,0,1] neg_hi:[0,0,1]
	v_pk_fma_f32 v[154:155], v[154:155], v[160:161], v[162:163]
	v_mov_b32_e32 v128, v104
	v_mov_b32_e32 v129, v105
	v_mov_b32_e32 v130, v106
	v_mov_b32_e32 v131, v107
	v_mov_b32_e32 v160, v108
	v_mov_b32_e32 v161, v109
	v_mov_b32_e32 v162, v110
	v_mov_b32_e32 v163, v111
	v_mov_b32_e32 v166, v129
	v_mov_b32_e32 v172, v160
	v_mov_b32_e32 v173, v163
	v_pk_mul_f32 v[170:171], v[170:171], v[172:173]
	v_mov_b32_e32 v172, v161
	v_mov_b32_e32 v164, v161
	v_mov_b32_e32 v165, v162
	v_pk_mul_f32 v[172:173], v[12:13], v[172:173]
	v_mov_b32_e32 v161, v162
	v_pk_fma_f32 v[162:163], v[4:5], v[160:161], v[172:173] neg_lo:[0,0,1] neg_hi:[0,0,1]
	v_pk_fma_f32 v[160:161], v[168:169], v[164:165], v[170:171]
	v_mov_b32_e32 v168, v14
	v_mov_b32_e32 v169, v7
	v_mov_b32_e32 v170, v128
	v_mov_b32_e32 v171, v131
	v_pk_mul_f32 v[168:169], v[168:169], v[170:171]
	v_mov_b32_e32 v170, v129
	v_mov_b32_e32 v167, v130
	v_mov_b32_e32 v164, v6
	v_mov_b32_e32 v165, v15
	v_pk_mul_f32 v[170:171], v[14:15], v[170:171]
	v_mov_b32_e32 v129, v130
	v_pk_fma_f32 v[130:131], v[6:7], v[128:129], v[170:171] neg_lo:[0,0,1] neg_hi:[0,0,1]
	v_pk_fma_f32 v[128:129], v[164:165], v[166:167], v[168:169]
